# SSM pass 2 scan: 20 multiply-add steps accumulate straight into the running state with chained pk_fma (one packed op fewer each)
# speedup vs baseline: 1.0032x; 1.0032x over previous
; __device__ __forceinline__ unsigned cvt_pk_bf16(float lo, float hi) { unsigned r; asm("v_cvt_pk_bf16_f32 %0, %1, %2" : "=v"(r) : "v"(lo), "v"(hi)); return r; }
; #define SSM_SCAN_STEP(D, SQ) { _Pragma("unroll") for (int r = 0; r < 4; ++r) { \
;                     const float sr = dppf<DPP_SHR(D)>(Er[r]), si = dppf<DPP_SHR(D)>(Ei[r]); \
;                     Er[r] += mr[r] * sr - mi[r] * si; Ei[r] += mr[r] * si + mi[r] * sr; \
;                     if (SQ) { const float nr = mr[r] * mr[r] - mi[r] * mi[r], ni = 2.f * mr[r] * mi[r]; mr[r] = nr; mi[r] = ni; } } }
; template <bool PASS2>
; __device__ __forceinline__ void ssm_phase(const Params& p, const Frame& F0) {
;     ...
;             for (int i = 0; i < 4; ++i) {
;                 __builtin_amdgcn_sched_barrier(0);
;                 f32x4 Er = (f32x4){0.f, 0.f, 0.f, 0.f}, Ei = Er;
; #pragma unroll
;                 for (int ks = 0; ks < 4; ++ks) { Er = __builtin_amdgcn_mfma_f32_16x16x32_bf16(frag[(i * 4 + ks) * 64], uf[ks], Er, 0, 0, 0);
;                                                  Ei = __builtin_amdgcn_mfma_f32_16x16x32_bf16(frag[((i + 4) * 4 + ks) * 64], uf[ks], Ei, 0, 0, 0); }
;                 const f32x4 ma = m1t[8 * i], mb = m1t[8 * i + 1];
;                 float mr[4] = {ma[0], ma[2], mb[0], mb[2]}, mi[4] = {ma[1], ma[3], mb[1], mb[3]};
;                 float hr[4], hi[4];
; #pragma unroll
;                 for (int r = 0; r < 4; ++r) { hr[r] = dppf<DPP_ROR(1)>(xs[i][r]); hi[r] = dppf<DPP_ROR(1)>(xs[i + 4][r]);
;                     if (j == 0) { Er[r] += mr[r] * hr[r] - mi[r] * hi[r]; Ei[r] += mr[r] * hi[r] + mi[r] * hr[r]; } }
;     ...
;                 SSM_SCAN_STEP(1, 1) SSM_SCAN_STEP(2, 1) SSM_SCAN_STEP(4, 1) SSM_SCAN_STEP(8, 0)
;     ...
;                 if constexpr (PASS2) {
;                     float vr[4], vi[4];
; #pragma unroll
;                     for (int r = 0; r < 4; ++r) { const float pr_ = dppf<DPP_ROR(1)>(Er[r]), pi_ = dppf<DPP_ROR(1)>(Ei[r]); vr[r] = (j == 0) ? hr[r] : pr_; vi[r] = (j == 0) ? hi[r] : pi_; }
;                     hw[i >> 1][2 * (i & 1)] = cvt_pk_bf16(vr[0], vr[1]); hw[i >> 1][2 * (i & 1) + 1] = cvt_pk_bf16(vr[2], vr[3]);
;                     hw[2 + (i >> 1)][2 * (i & 1)] = cvt_pk_bf16(vi[0], vi[1]); hw[2 + (i >> 1)][2 * (i & 1) + 1] = cvt_pk_bf16(vi[2], vi[3]);
;                 }
;                 xs[i] = Er; xs[i + 4] = Ei;
.Lssmw_2:
	ds_read_b128 v[84:87], v105 offset:3072
	ds_read_b128 v[88:91], v105 offset:19456
	s_waitcnt lgkmcnt(2)
	v_mfma_f32_16x16x32_bf16 v[76:79], v[80:83], v[64:67], v[76:79]
	v_mov_b32_dpp v83, v38 row_ror:1 row_mask:0xf bank_mask:0xf bound_ctrl:1
	v_mov_b32_dpp v82, v42 row_ror:1 row_mask:0xf bank_mask:0xf bound_ctrl:1
	v_mfma_f32_16x16x32_bf16 v[68:71], v[72:75], v[64:67], v[68:71]
	ds_read_b128 v[72:75], v198
	ds_read_b128 v[204:207], v198 offset:16
	ds_read_b128 v[208:211], v198 offset:1024
	ds_read_b128 v[212:215], v198 offset:1536
	s_waitcnt lgkmcnt(3)
	v_pk_mul_f32 v[80:81], v[72:73], v[2:3] op_sel:[0,1] op_sel_hi:[1,0]
	v_mfma_f32_16x16x32_bf16 v[76:79], v[88:91], v[60:63], v[76:79]
	v_sub_f32_e32 v1, v80, v81
	v_pk_mul_f32 v[80:81], v[72:73], v[2:3]
	v_mov_b32_e32 v90, v73
	v_mfma_f32_16x16x32_bf16 v[68:71], v[84:87], v[60:63], v[68:71]
	v_add_f32_e32 v36, v81, v80
	v_mov_b32_dpp v81, v37 row_ror:1 row_mask:0xf bank_mask:0xf bound_ctrl:1
	v_mov_b32_dpp v80, v41 row_ror:1 row_mask:0xf bank_mask:0xf bound_ctrl:1
	s_nop 0
	v_add_f32_e32 v40, v76, v36
	v_pk_mul_f32 v[36:37], v[74:75], v[80:81] op_sel:[0,1] op_sel_hi:[1,0]
	v_mov_b32_dpp v85, v39 row_ror:1 row_mask:0xf bank_mask:0xf bound_ctrl:1
	v_sub_f32_e32 v36, v36, v37
	v_add_f32_e32 v41, v36, v69
	v_pk_mul_f32 v[36:37], v[74:75], v[80:81]
	v_mov_b32_dpp v84, v43 row_ror:1 row_mask:0xf bank_mask:0xf bound_ctrl:1
	v_add_f32_e32 v36, v37, v36
	v_add_f32_e32 v86, v36, v77
	s_waitcnt lgkmcnt(2)
	v_pk_mul_f32 v[36:37], v[204:205], v[82:83] op_sel:[0,1] op_sel_hi:[1,0]
	v_add_f32_e32 v1, v68, v1
	v_sub_f32_e32 v36, v36, v37
	v_add_f32_e32 v42, v36, v70
	v_pk_mul_f32 v[36:37], v[204:205], v[82:83]
	v_cndmask_b32_e64 v42, v70, v42, s[10:11]
	v_add_f32_e32 v36, v37, v36
	v_add_f32_e32 v38, v36, v78
	v_pk_mul_f32 v[36:37], v[206:207], v[84:85] op_sel:[0,1] op_sel_hi:[1,0]
	v_cndmask_b32_e64 v41, v69, v41, s[10:11]
	v_sub_f32_e32 v36, v36, v37
	v_add_f32_e32 v43, v36, v71
	v_pk_mul_f32 v[36:37], v[206:207], v[84:85]
	v_cndmask_b32_e64 v43, v71, v43, s[10:11]
	v_add_f32_e32 v36, v37, v36
	v_add_f32_e32 v36, v36, v79
	v_cndmask_b32_e64 v39, v79, v36, s[10:11]
	v_cndmask_b32_e64 v37, v77, v86, s[10:11]
	v_cndmask_b32_e64 v36, v76, v40, s[10:11]
	v_cndmask_b32_e64 v40, v68, v1, s[10:11]
	v_mov_b32_dpp v71, v37 row_shr:1 row_mask:0xf bank_mask:0xf bound_ctrl:1
	v_mov_b32_dpp v70, v36 row_shr:1 row_mask:0xf bank_mask:0xf bound_ctrl:1
	v_mov_b32_e32 v86, v72
	v_mov_b32_e32 v87, v74
	v_mov_b32_dpp v68, v40 row_shr:1 row_mask:0xf bank_mask:0xf bound_ctrl:1
	v_mov_b32_dpp v69, v41 row_shr:1 row_mask:0xf bank_mask:0xf bound_ctrl:1
	v_pk_mul_f32 v[88:89], v[86:87], v[70:71]
	v_mov_b32_e32 v91, v75
	ds_read_b128 v[72:75], v198 offset:512
	v_pk_fma_f32 v[88:89], v[90:91], v[68:69], v[88:89]
	v_pk_add_f32 v[36:37], v[88:89], v[36:37]
	v_pk_fma_f32 v[40:41], v[90:91], v[70:71], v[40:41] neg_lo:[1,0,0] neg_hi:[1,0,0]
	ds_read_b64 v[90:91], v198 offset:1040
	v_pk_fma_f32 v[40:41], v[86:87], v[68:69], v[40:41]
	v_mov_b32_dpp v88, v36 row_shr:2 row_mask:0xf bank_mask:0xf bound_ctrl:1
	v_mov_b32_dpp v89, v37 row_shr:2 row_mask:0xf bank_mask:0xf bound_ctrl:1
	s_waitcnt lgkmcnt(1)
	v_pk_fma_f32 v[36:37], v[72:73], v[88:89], v[36:37]
	v_pk_mul_f32 v[70:71], v[74:75], v[88:89]
	v_mov_b32_dpp v68, v40 row_shr:2 row_mask:0xf bank_mask:0xf bound_ctrl:1
	v_mov_b32_dpp v69, v41 row_shr:2 row_mask:0xf bank_mask:0xf bound_ctrl:1
	v_pk_fma_f32 v[70:71], v[72:73], v[68:69], v[70:71] neg_lo:[0,0,1] neg_hi:[0,0,1]
	v_pk_fma_f32 v[36:37], v[74:75], v[68:69], v[36:37]
	ds_read_b64 v[74:75], v198 offset:536
	ds_read_b64 v[200:201], v198 offset:1048
	v_pk_add_f32 v[40:41], v[70:71], v[40:41]
	s_nop 0
	v_mov_b32_dpp v70, v36 row_shr:4 row_mask:0xf bank_mask:0xf bound_ctrl:1
	v_mov_b32_dpp v71, v37 row_shr:4 row_mask:0xf bank_mask:0xf bound_ctrl:1
	v_mov_b32_dpp v68, v40 row_shr:4 row_mask:0xf bank_mask:0xf bound_ctrl:1
	v_mov_b32_dpp v69, v41 row_shr:4 row_mask:0xf bank_mask:0xf bound_ctrl:1
	v_pk_mul_f32 v[72:73], v[210:211], v[70:71]
	v_pk_mul_f32 v[70:71], v[208:209], v[70:71]
	v_pk_fma_f32 v[72:73], v[208:209], v[68:69], v[72:73] neg_lo:[0,0,1] neg_hi:[0,0,1]
	v_pk_fma_f32 v[68:69], v[210:211], v[68:69], v[70:71]
	v_pk_add_f32 v[68:69], v[36:37], v[68:69]
	v_pk_add_f32 v[40:41], v[40:41], v[72:73]
	s_nop 0
	v_mov_b32_dpp v72, v68 row_shr:8 row_mask:0xf bank_mask:0xf bound_ctrl:1
	v_mov_b32_dpp v73, v69 row_shr:8 row_mask:0xf bank_mask:0xf bound_ctrl:1
	v_mov_b32_dpp v70, v40 row_shr:8 row_mask:0xf bank_mask:0xf bound_ctrl:1
	v_mov_b32_dpp v71, v41 row_shr:8 row_mask:0xf bank_mask:0xf bound_ctrl:1
	v_pk_mul_f32 v[36:37], v[214:215], v[72:73]
	v_cndmask_b32_e64 v38, v78, v38, s[10:11]
	v_pk_fma_f32 v[36:37], v[212:213], v[70:71], v[36:37] neg_lo:[0,0,1] neg_hi:[0,0,1]
	v_mov_b32_dpp v79, v39 row_shr:1 row_mask:0xf bank_mask:0xf bound_ctrl:1
	v_pk_add_f32 v[36:37], v[40:41], v[36:37]
	v_pk_mul_f32 v[40:41], v[212:213], v[72:73]
	v_mov_b32_dpp v78, v38 row_shr:1 row_mask:0xf bank_mask:0xf bound_ctrl:1
	v_pk_fma_f32 v[40:41], v[214:215], v[70:71], v[40:41]
	v_mov_b32_dpp v76, v42 row_shr:1 row_mask:0xf bank_mask:0xf bound_ctrl:1
	v_pk_add_f32 v[40:41], v[68:69], v[40:41]
	v_mov_b32_e32 v68, v204
	v_mov_b32_e32 v69, v206
	v_mov_b32_dpp v77, v43 row_shr:1 row_mask:0xf bank_mask:0xf bound_ctrl:1
	v_pk_mul_f32 v[70:71], v[68:69], v[78:79]
	v_mov_b32_e32 v72, v205
	v_mov_b32_e32 v73, v207
	ds_read_b128 v[204:207], v198 offset:1552
	v_pk_fma_f32 v[70:71], v[72:73], v[76:77], v[70:71]
	v_pk_add_f32 v[38:39], v[70:71], v[38:39]
	ds_read_b64 v[70:71], v198 offset:528
	v_pk_fma_f32 v[42:43], v[72:73], v[78:79], v[42:43] neg_lo:[1,0,0] neg_hi:[1,0,0]
	v_mov_b32_dpp v86, v38 row_shr:2 row_mask:0xf bank_mask:0xf bound_ctrl:1
	v_pk_fma_f32 v[42:43], v[68:69], v[76:77], v[42:43]
	v_mov_b32_dpp v87, v39 row_shr:2 row_mask:0xf bank_mask:0xf bound_ctrl:1
	s_waitcnt lgkmcnt(0)
; __device__ __forceinline__ unsigned cvt_pk_bf16(float lo, float hi) { unsigned r; asm("v_cvt_pk_bf16_f32 %0, %1, %2" : "=v"(r) : "v"(lo), "v"(hi)); return r; }
; #define SSM_SCAN_STEP(D, SQ) { _Pragma("unroll") for (int r = 0; r < 4; ++r) { \
;                     const float sr = dppf<DPP_SHR(D)>(Er[r]), si = dppf<DPP_SHR(D)>(Ei[r]); \
;                     Er[r] += mr[r] * sr - mi[r] * si; Ei[r] += mr[r] * si + mi[r] * sr; \
;                     if (SQ) { const float nr = mr[r] * mr[r] - mi[r] * mi[r], ni = 2.f * mr[r] * mi[r]; mr[r] = nr; mi[r] = ni; } } }
; template <bool PASS2>
; __device__ __forceinline__ void ssm_phase(const Params& p, const Frame& F0) {
;     ...
;             for (int i = 0; i < 4; ++i) {
;                 __builtin_amdgcn_sched_barrier(0);
;                 f32x4 Er = (f32x4){0.f, 0.f, 0.f, 0.f}, Ei = Er;
; #pragma unroll
;                 for (int ks = 0; ks < 4; ++ks) { Er = __builtin_amdgcn_mfma_f32_16x16x32_bf16(frag[(i * 4 + ks) * 64], uf[ks], Er, 0, 0, 0);
;                                                  Ei = __builtin_amdgcn_mfma_f32_16x16x32_bf16(frag[((i + 4) * 4 + ks) * 64], uf[ks], Ei, 0, 0, 0); }
;                 const f32x4 ma = m1t[8 * i], mb = m1t[8 * i + 1];
;                 float mr[4] = {ma[0], ma[2], mb[0], mb[2]}, mi[4] = {ma[1], ma[3], mb[1], mb[3]};
;                 float hr[4], hi[4];
; #pragma unroll
;                 for (int r = 0; r < 4; ++r) { hr[r] = dppf<DPP_ROR(1)>(xs[i][r]); hi[r] = dppf<DPP_ROR(1)>(xs[i + 4][r]);
;                     if (j == 0) { Er[r] += mr[r] * hr[r] - mi[r] * hi[r]; Ei[r] += mr[r] * hi[r] + mi[r] * hr[r]; } }
;     ...
;                 SSM_SCAN_STEP(1, 1) SSM_SCAN_STEP(2, 1) SSM_SCAN_STEP(4, 1) SSM_SCAN_STEP(8, 0)
;     ...
;                 if constexpr (PASS2) {
;                     float vr[4], vi[4];
; #pragma unroll
;                     for (int r = 0; r < 4; ++r) { const float pr_ = dppf<DPP_ROR(1)>(Er[r]), pi_ = dppf<DPP_ROR(1)>(Ei[r]); vr[r] = (j == 0) ? hr[r] : pr_; vi[r] = (j == 0) ? hi[r] : pi_; }
;                     hw[i >> 1][2 * (i & 1)] = cvt_pk_bf16(vr[0], vr[1]); hw[i >> 1][2 * (i & 1) + 1] = cvt_pk_bf16(vr[2], vr[3]);
;                     hw[2 + (i >> 1)][2 * (i & 1)] = cvt_pk_bf16(vi[0], vi[1]); hw[2 + (i >> 1)][2 * (i & 1) + 1] = cvt_pk_bf16(vi[2], vi[3]);
;                 }
;                 xs[i] = Er; xs[i + 4] = Ei;
	v_pk_fma_f32 v[38:39], v[70:71], v[86:87], v[38:39]
	v_mov_b32_dpp v68, v42 row_shr:2 row_mask:0xf bank_mask:0xf bound_ctrl:1
	v_mov_b32_dpp v69, v43 row_shr:2 row_mask:0xf bank_mask:0xf bound_ctrl:1
	v_pk_fma_f32 v[42:43], v[74:75], v[86:87], v[42:43] neg_lo:[1,0,0] neg_hi:[1,0,0]
	v_pk_fma_f32 v[42:43], v[70:71], v[68:69], v[42:43]
	v_pk_fma_f32 v[38:39], v[74:75], v[68:69], v[38:39]
	s_nop 0
	s_nop 0
	v_mov_b32_dpp v70, v38 row_shr:4 row_mask:0xf bank_mask:0xf bound_ctrl:1
	v_mov_b32_dpp v71, v39 row_shr:4 row_mask:0xf bank_mask:0xf bound_ctrl:1
	v_mov_b32_dpp v68, v42 row_shr:4 row_mask:0xf bank_mask:0xf bound_ctrl:1
	v_mov_b32_dpp v69, v43 row_shr:4 row_mask:0xf bank_mask:0xf bound_ctrl:1
	v_pk_mul_f32 v[72:73], v[200:201], v[70:71]
	v_pk_mul_f32 v[70:71], v[90:91], v[70:71]
	v_pk_fma_f32 v[72:73], v[90:91], v[68:69], v[72:73] neg_lo:[0,0,1] neg_hi:[0,0,1]
	v_pk_fma_f32 v[68:69], v[200:201], v[68:69], v[70:71]
	v_pk_add_f32 v[68:69], v[38:39], v[68:69]
	v_pk_add_f32 v[42:43], v[42:43], v[72:73]
	s_nop 0
	v_mov_b32_dpp v72, v68 row_shr:8 row_mask:0xf bank_mask:0xf bound_ctrl:1
	v_mov_b32_dpp v73, v69 row_shr:8 row_mask:0xf bank_mask:0xf bound_ctrl:1
	v_mov_b32_dpp v70, v42 row_shr:8 row_mask:0xf bank_mask:0xf bound_ctrl:1
	v_mov_b32_dpp v71, v43 row_shr:8 row_mask:0xf bank_mask:0xf bound_ctrl:1
	v_pk_mul_f32 v[38:39], v[206:207], v[72:73]
	v_mov_b32_dpp v1, v36 row_ror:1 row_mask:0xf bank_mask:0xf bound_ctrl:1
	v_pk_fma_f32 v[38:39], v[204:205], v[70:71], v[38:39] neg_lo:[0,0,1] neg_hi:[0,0,1]
	v_cndmask_b32_e64 v1, v1, v3, s[10:11]
	v_pk_add_f32 v[38:39], v[42:43], v[38:39]
	v_pk_mul_f32 v[42:43], v[204:205], v[72:73]
	v_mov_b32_dpp v3, v37 row_ror:1 row_mask:0xf bank_mask:0xf bound_ctrl:1
	v_pk_fma_f32 v[42:43], v[206:207], v[70:71], v[42:43]
	v_mov_b32_dpp v71, v39 row_ror:1 row_mask:0xf bank_mask:0xf bound_ctrl:1
	v_pk_add_f32 v[42:43], v[68:69], v[42:43]
	v_mov_b32_dpp v68, v40 row_ror:1 row_mask:0xf bank_mask:0xf bound_ctrl:1
	v_cndmask_b32_e64 v2, v68, v2, s[10:11]
	v_mov_b32_dpp v69, v38 row_ror:1 row_mask:0xf bank_mask:0xf bound_ctrl:1
	v_mov_b32_dpp v68, v41 row_ror:1 row_mask:0xf bank_mask:0xf bound_ctrl:1
	v_mov_b32_dpp v70, v42 row_ror:1 row_mask:0xf bank_mask:0xf bound_ctrl:1
	v_mov_b32_dpp v72, v43 row_ror:1 row_mask:0xf bank_mask:0xf bound_ctrl:1
	v_cndmask_b32_e64 v68, v68, v80, s[10:11]
	v_cndmask_b32_e64 v69, v69, v83, s[10:11]
	v_cndmask_b32_e64 v70, v70, v82, s[10:11]
	v_cndmask_b32_e64 v71, v71, v85, s[10:11]
	v_cndmask_b32_e64 v74, v72, v84, s[10:11]
	v_cndmask_b32_e64 v3, v3, v81, s[10:11]
	v_cvt_pk_bf16_f32 v72, v1, v3
	v_cvt_pk_bf16_f32 v73, v69, v71
	v_cvt_pk_bf16_f32 v68, v2, v68
	v_cvt_pk_bf16_f32 v69, v70, v74
	ds_read_b128 v[74:77], v105 offset:4096
	ds_read_b128 v[78:81], v105 offset:5120
	ds_read_b128 v[82:85], v105 offset:20480
	ds_read_b128 v[86:89], v105 offset:21504
	v_mov_b32_dpp v3, v28 row_ror:1 row_mask:0xf bank_mask:0xf bound_ctrl:1
	s_and_b32 s98, s3, 0x180
	s_cbranch_scc1 .Lssmw_3
	s_waitcnt vmcnt(4)
.Lssmw_3:
	v_mov_b32_dpp v2, v32 row_ror:1 row_mask:0xf bank_mask:0xf bound_ctrl:1
	s_waitcnt lgkmcnt(3)
	v_mfma_f32_16x16x32_bf16 v[74:77], v[74:77], v[56:59], 0
	s_waitcnt lgkmcnt(1)
	v_mfma_f32_16x16x32_bf16 v[82:85], v[82:85], v[56:59], 0
	v_mfma_f32_16x16x32_bf16 v[74:77], v[78:81], v[52:55], v[74:77]
	ds_read_b128 v[78:81], v105 offset:6144
	s_waitcnt lgkmcnt(1)
	v_mfma_f32_16x16x32_bf16 v[82:85], v[86:89], v[52:55], v[82:85]
	ds_read_b128 v[86:89], v105 offset:22528
	ds_read_b128 v[204:207], v105 offset:7168
	ds_read_b128 v[208:211], v105 offset:23552
	s_waitcnt lgkmcnt(2)
	v_mfma_f32_16x16x32_bf16 v[82:85], v[86:89], v[64:67], v[82:85]
	v_mov_b32_dpp v87, v30 row_ror:1 row_mask:0xf bank_mask:0xf bound_ctrl:1
	v_mov_b32_dpp v86, v34 row_ror:1 row_mask:0xf bank_mask:0xf bound_ctrl:1
	v_mov_b32_dpp v89, v31 row_ror:1 row_mask:0xf bank_mask:0xf bound_ctrl:1
	v_mfma_f32_16x16x32_bf16 v[74:77], v[78:81], v[64:67], v[74:77]
	ds_read_b128 v[78:81], v198 offset:128
	ds_read_b128 v[212:215], v198 offset:144
	ds_read_b128 v[216:219], v198 offset:1664
	v_mov_b32_dpp v88, v35 row_ror:1 row_mask:0xf bank_mask:0xf bound_ctrl:1
	s_waitcnt lgkmcnt(2)
	v_pk_mul_f32 v[70:71], v[78:79], v[2:3] op_sel:[0,1] op_sel_hi:[1,0]
	v_mfma_f32_16x16x32_bf16 v[82:85], v[208:211], v[60:63], v[82:85]
	ds_read_b128 v[208:211], v198 offset:1152
	v_sub_f32_e32 v1, v70, v71
	v_pk_mul_f32 v[70:71], v[78:79], v[2:3]
	v_mov_b32_e32 v91, v80
	v_mfma_f32_16x16x32_bf16 v[74:77], v[204:207], v[60:63], v[74:77]
	v_add_f32_e32 v28, v71, v70
	v_mov_b32_dpp v71, v29 row_ror:1 row_mask:0xf bank_mask:0xf bound_ctrl:1
	v_mov_b32_dpp v70, v33 row_ror:1 row_mask:0xf bank_mask:0xf bound_ctrl:1
	s_nop 0
	v_add_f32_e32 v32, v82, v28
	v_pk_mul_f32 v[28:29], v[80:81], v[70:71] op_sel:[0,1] op_sel_hi:[1,0]
	s_nop 1
	v_add_f32_e32 v1, v74, v1
	v_sub_f32_e32 v28, v28, v29
	v_add_f32_e32 v33, v28, v75
	v_pk_mul_f32 v[28:29], v[80:81], v[70:71]
	v_cndmask_b32_e64 v33, v75, v33, s[10:11]
	v_add_f32_e32 v28, v29, v28
	v_add_f32_e32 v90, v28, v83
	s_waitcnt lgkmcnt(2)
; #define SSM_SCAN_STEP(D, SQ) { _Pragma("unroll") for (int r = 0; r < 4; ++r) { \
;                     const float sr = dppf<DPP_SHR(D)>(Er[r]), si = dppf<DPP_SHR(D)>(Ei[r]); \
;                     Er[r] += mr[r] * sr - mi[r] * si; Ei[r] += mr[r] * si + mi[r] * sr; \
;                     if (SQ) { const float nr = mr[r] * mr[r] - mi[r] * mi[r], ni = 2.f * mr[r] * mi[r]; mr[r] = nr; mi[r] = ni; } } }
; template <bool PASS2>
; __device__ __forceinline__ void ssm_phase(const Params& p, const Frame& F0) {
;     ...
;             for (int i = 0; i < 4; ++i) {
;                 __builtin_amdgcn_sched_barrier(0);
;                 f32x4 Er = (f32x4){0.f, 0.f, 0.f, 0.f}, Ei = Er;
; #pragma unroll
;                 for (int ks = 0; ks < 4; ++ks) { Er = __builtin_amdgcn_mfma_f32_16x16x32_bf16(frag[(i * 4 + ks) * 64], uf[ks], Er, 0, 0, 0);
;                                                  Ei = __builtin_amdgcn_mfma_f32_16x16x32_bf16(frag[((i + 4) * 4 + ks) * 64], uf[ks], Ei, 0, 0, 0); }
;                 const f32x4 ma = m1t[8 * i], mb = m1t[8 * i + 1];
;                 float mr[4] = {ma[0], ma[2], mb[0], mb[2]}, mi[4] = {ma[1], ma[3], mb[1], mb[3]};
;                 float hr[4], hi[4];
; #pragma unroll
;                 for (int r = 0; r < 4; ++r) { hr[r] = dppf<DPP_ROR(1)>(xs[i][r]); hi[r] = dppf<DPP_ROR(1)>(xs[i + 4][r]);
;                     if (j == 0) { Er[r] += mr[r] * hr[r] - mi[r] * hi[r]; Ei[r] += mr[r] * hi[r] + mi[r] * hr[r]; } }
;     ...
;                 SSM_SCAN_STEP(1, 1) SSM_SCAN_STEP(2, 1) SSM_SCAN_STEP(4, 1) SSM_SCAN_STEP(8, 0)
	v_pk_mul_f32 v[28:29], v[212:213], v[86:87] op_sel:[0,1] op_sel_hi:[1,0]
	v_mov_b32_dpp v75, v33 row_shr:1 row_mask:0xf bank_mask:0xf bound_ctrl:1
	v_sub_f32_e32 v28, v28, v29
	v_add_f32_e32 v34, v28, v76
	v_pk_mul_f32 v[28:29], v[212:213], v[86:87]
	v_cndmask_b32_e64 v34, v76, v34, s[10:11]
	v_add_f32_e32 v28, v29, v28
	v_add_f32_e32 v30, v28, v84
	v_pk_mul_f32 v[28:29], v[214:215], v[88:89] op_sel:[0,1] op_sel_hi:[1,0]
	v_mov_b32_e32 v204, v79
	v_sub_f32_e32 v28, v28, v29
	v_add_f32_e32 v35, v28, v77
	v_pk_mul_f32 v[28:29], v[214:215], v[88:89]
	v_cndmask_b32_e64 v35, v77, v35, s[10:11]
	v_add_f32_e32 v28, v29, v28
	v_add_f32_e32 v28, v28, v85
	v_cndmask_b32_e64 v31, v85, v28, s[10:11]
	v_cndmask_b32_e64 v29, v83, v90, s[10:11]
	v_cndmask_b32_e64 v28, v82, v32, s[10:11]
	v_cndmask_b32_e64 v32, v74, v1, s[10:11]
	v_mov_b32_dpp v77, v29 row_shr:1 row_mask:0xf bank_mask:0xf bound_ctrl:1
	v_mov_b32_dpp v76, v28 row_shr:1 row_mask:0xf bank_mask:0xf bound_ctrl:1
	v_mov_b32_e32 v90, v78
	v_mov_b32_dpp v74, v32 row_shr:1 row_mask:0xf bank_mask:0xf bound_ctrl:1
	v_pk_mul_f32 v[200:201], v[90:91], v[76:77]
	v_mov_b32_e32 v205, v81
	ds_read_b128 v[78:81], v198 offset:640
	v_pk_fma_f32 v[200:201], v[204:205], v[74:75], v[200:201]
	v_pk_add_f32 v[28:29], v[200:201], v[28:29]
	v_pk_fma_f32 v[32:33], v[204:205], v[76:77], v[32:33] neg_lo:[1,0,0] neg_hi:[1,0,0]
	v_pk_fma_f32 v[32:33], v[90:91], v[74:75], v[32:33]
	v_mov_b32_dpp v200, v28 row_shr:2 row_mask:0xf bank_mask:0xf bound_ctrl:1
	v_mov_b32_dpp v201, v29 row_shr:2 row_mask:0xf bank_mask:0xf bound_ctrl:1
	s_waitcnt lgkmcnt(0)
	v_pk_fma_f32 v[28:29], v[78:79], v[200:201], v[28:29]
	v_pk_mul_f32 v[76:77], v[80:81], v[200:201]
	v_mov_b32_dpp v74, v32 row_shr:2 row_mask:0xf bank_mask:0xf bound_ctrl:1
	v_mov_b32_dpp v75, v33 row_shr:2 row_mask:0xf bank_mask:0xf bound_ctrl:1
	v_pk_fma_f32 v[76:77], v[78:79], v[74:75], v[76:77] neg_lo:[0,0,1] neg_hi:[0,0,1]
	v_pk_fma_f32 v[28:29], v[80:81], v[74:75], v[28:29]
	ds_read_b64 v[80:81], v198 offset:664
	ds_read_b128 v[204:207], v198 offset:1168
	v_pk_add_f32 v[32:33], v[76:77], v[32:33]
	s_nop 0
	v_mov_b32_dpp v76, v28 row_shr:4 row_mask:0xf bank_mask:0xf bound_ctrl:1
	v_mov_b32_dpp v77, v29 row_shr:4 row_mask:0xf bank_mask:0xf bound_ctrl:1
	v_mov_b32_dpp v74, v32 row_shr:4 row_mask:0xf bank_mask:0xf bound_ctrl:1
	v_mov_b32_dpp v75, v33 row_shr:4 row_mask:0xf bank_mask:0xf bound_ctrl:1
	v_pk_mul_f32 v[78:79], v[210:211], v[76:77]
	v_pk_mul_f32 v[76:77], v[208:209], v[76:77]
	v_pk_fma_f32 v[78:79], v[208:209], v[74:75], v[78:79] neg_lo:[0,0,1] neg_hi:[0,0,1]
	v_pk_fma_f32 v[74:75], v[210:211], v[74:75], v[76:77]
	ds_read_b128 v[208:211], v198 offset:1680
	v_pk_add_f32 v[74:75], v[28:29], v[74:75]
	v_pk_add_f32 v[32:33], v[32:33], v[78:79]
	s_nop 0
	v_mov_b32_dpp v78, v74 row_shr:8 row_mask:0xf bank_mask:0xf bound_ctrl:1
	v_mov_b32_dpp v79, v75 row_shr:8 row_mask:0xf bank_mask:0xf bound_ctrl:1
	v_mov_b32_dpp v76, v32 row_shr:8 row_mask:0xf bank_mask:0xf bound_ctrl:1
	v_mov_b32_dpp v77, v33 row_shr:8 row_mask:0xf bank_mask:0xf bound_ctrl:1
	v_pk_mul_f32 v[28:29], v[218:219], v[78:79]
	v_cndmask_b32_e64 v30, v84, v30, s[10:11]
	v_pk_fma_f32 v[28:29], v[216:217], v[76:77], v[28:29] neg_lo:[0,0,1] neg_hi:[0,0,1]
	v_mov_b32_dpp v85, v31 row_shr:1 row_mask:0xf bank_mask:0xf bound_ctrl:1
	v_pk_add_f32 v[28:29], v[32:33], v[28:29]
	v_pk_mul_f32 v[32:33], v[216:217], v[78:79]
	v_mov_b32_dpp v84, v30 row_shr:1 row_mask:0xf bank_mask:0xf bound_ctrl:1
	v_pk_fma_f32 v[32:33], v[218:219], v[76:77], v[32:33]
	v_mov_b32_dpp v82, v34 row_shr:1 row_mask:0xf bank_mask:0xf bound_ctrl:1
	v_pk_add_f32 v[32:33], v[74:75], v[32:33]
	v_mov_b32_e32 v74, v212
	v_mov_b32_e32 v75, v214
	v_mov_b32_dpp v83, v35 row_shr:1 row_mask:0xf bank_mask:0xf bound_ctrl:1
	v_pk_mul_f32 v[76:77], v[74:75], v[84:85]
	v_mov_b32_e32 v78, v213
	v_mov_b32_e32 v79, v215
	v_pk_fma_f32 v[76:77], v[78:79], v[82:83], v[76:77]
	v_pk_add_f32 v[30:31], v[76:77], v[30:31]
	ds_read_b64 v[76:77], v198 offset:656
	v_pk_fma_f32 v[34:35], v[78:79], v[84:85], v[34:35] neg_lo:[1,0,0] neg_hi:[1,0,0]
	v_mov_b32_dpp v90, v30 row_shr:2 row_mask:0xf bank_mask:0xf bound_ctrl:1
	v_pk_fma_f32 v[34:35], v[74:75], v[82:83], v[34:35]
	v_mov_b32_dpp v91, v31 row_shr:2 row_mask:0xf bank_mask:0xf bound_ctrl:1
	s_waitcnt lgkmcnt(0)
; __device__ __forceinline__ unsigned cvt_pk_bf16(float lo, float hi) { unsigned r; asm("v_cvt_pk_bf16_f32 %0, %1, %2" : "=v"(r) : "v"(lo), "v"(hi)); return r; }
; #define SSM_SCAN_STEP(D, SQ) { _Pragma("unroll") for (int r = 0; r < 4; ++r) { \
;                     const float sr = dppf<DPP_SHR(D)>(Er[r]), si = dppf<DPP_SHR(D)>(Ei[r]); \
;                     Er[r] += mr[r] * sr - mi[r] * si; Ei[r] += mr[r] * si + mi[r] * sr; \
;                     if (SQ) { const float nr = mr[r] * mr[r] - mi[r] * mi[r], ni = 2.f * mr[r] * mi[r]; mr[r] = nr; mi[r] = ni; } } }
; template <bool PASS2>
; __device__ __forceinline__ void ssm_phase(const Params& p, const Frame& F0) {
;     ...
;                 SSM_SCAN_STEP(1, 1) SSM_SCAN_STEP(2, 1) SSM_SCAN_STEP(4, 1) SSM_SCAN_STEP(8, 0)
;     ...
;                 if constexpr (PASS2) {
;                     float vr[4], vi[4];
; #pragma unroll
;                     for (int r = 0; r < 4; ++r) { const float pr_ = dppf<DPP_ROR(1)>(Er[r]), pi_ = dppf<DPP_ROR(1)>(Ei[r]); vr[r] = (j == 0) ? hr[r] : pr_; vi[r] = (j == 0) ? hi[r] : pi_; }
;                     hw[i >> 1][2 * (i & 1)] = cvt_pk_bf16(vr[0], vr[1]); hw[i >> 1][2 * (i & 1) + 1] = cvt_pk_bf16(vr[2], vr[3]);
;                     hw[2 + (i >> 1)][2 * (i & 1)] = cvt_pk_bf16(vi[0], vi[1]); hw[2 + (i >> 1)][2 * (i & 1) + 1] = cvt_pk_bf16(vi[2], vi[3]);
;                 }
	v_pk_fma_f32 v[30:31], v[76:77], v[90:91], v[30:31]
	v_mov_b32_dpp v74, v34 row_shr:2 row_mask:0xf bank_mask:0xf bound_ctrl:1
	v_mov_b32_dpp v75, v35 row_shr:2 row_mask:0xf bank_mask:0xf bound_ctrl:1
	v_pk_fma_f32 v[34:35], v[80:81], v[90:91], v[34:35] neg_lo:[1,0,0] neg_hi:[1,0,0]
	v_pk_fma_f32 v[34:35], v[76:77], v[74:75], v[34:35]
	v_pk_fma_f32 v[30:31], v[80:81], v[74:75], v[30:31]
	s_nop 0
	s_nop 0
	v_mov_b32_dpp v76, v30 row_shr:4 row_mask:0xf bank_mask:0xf bound_ctrl:1
	v_mov_b32_dpp v77, v31 row_shr:4 row_mask:0xf bank_mask:0xf bound_ctrl:1
	v_mov_b32_dpp v74, v34 row_shr:4 row_mask:0xf bank_mask:0xf bound_ctrl:1
	v_mov_b32_dpp v75, v35 row_shr:4 row_mask:0xf bank_mask:0xf bound_ctrl:1
	v_pk_mul_f32 v[78:79], v[206:207], v[76:77]
	v_pk_mul_f32 v[76:77], v[204:205], v[76:77]
	v_pk_fma_f32 v[78:79], v[204:205], v[74:75], v[78:79] neg_lo:[0,0,1] neg_hi:[0,0,1]
	v_pk_fma_f32 v[74:75], v[206:207], v[74:75], v[76:77]
	v_pk_add_f32 v[74:75], v[30:31], v[74:75]
	v_pk_add_f32 v[34:35], v[34:35], v[78:79]
	s_nop 0
	v_mov_b32_dpp v78, v74 row_shr:8 row_mask:0xf bank_mask:0xf bound_ctrl:1
	v_mov_b32_dpp v79, v75 row_shr:8 row_mask:0xf bank_mask:0xf bound_ctrl:1
	v_mov_b32_dpp v76, v34 row_shr:8 row_mask:0xf bank_mask:0xf bound_ctrl:1
	v_mov_b32_dpp v77, v35 row_shr:8 row_mask:0xf bank_mask:0xf bound_ctrl:1
	v_pk_mul_f32 v[30:31], v[210:211], v[78:79]
	v_mov_b32_dpp v1, v28 row_ror:1 row_mask:0xf bank_mask:0xf bound_ctrl:1
	v_pk_fma_f32 v[30:31], v[208:209], v[76:77], v[30:31] neg_lo:[0,0,1] neg_hi:[0,0,1]
	v_cndmask_b32_e64 v1, v1, v3, s[10:11]
	v_pk_add_f32 v[30:31], v[34:35], v[30:31]
	v_pk_mul_f32 v[34:35], v[208:209], v[78:79]
	v_mov_b32_dpp v3, v29 row_ror:1 row_mask:0xf bank_mask:0xf bound_ctrl:1
	v_pk_fma_f32 v[34:35], v[210:211], v[76:77], v[34:35]
	v_cndmask_b32_e64 v3, v3, v71, s[10:11]
	v_pk_add_f32 v[34:35], v[74:75], v[34:35]
	v_mov_b32_dpp v74, v32 row_ror:1 row_mask:0xf bank_mask:0xf bound_ctrl:1
	v_cndmask_b32_e64 v2, v74, v2, s[10:11]
	v_mov_b32_dpp v71, v30 row_ror:1 row_mask:0xf bank_mask:0xf bound_ctrl:1
	v_mov_b32_dpp v74, v33 row_ror:1 row_mask:0xf bank_mask:0xf bound_ctrl:1
	v_cndmask_b32_e64 v70, v74, v70, s[10:11]
	v_mov_b32_dpp v75, v35 row_ror:1 row_mask:0xf bank_mask:0xf bound_ctrl:1
	v_mov_b32_dpp v74, v34 row_ror:1 row_mask:0xf bank_mask:0xf bound_ctrl:1
	v_cndmask_b32_e64 v76, v74, v86, s[10:11]
	v_cndmask_b32_e64 v71, v71, v87, s[10:11]
	v_mov_b32_dpp v74, v31 row_ror:1 row_mask:0xf bank_mask:0xf bound_ctrl:1
	v_cndmask_b32_e64 v77, v74, v89, s[10:11]
	v_cndmask_b32_e64 v78, v75, v88, s[10:11]
	v_cvt_pk_bf16_f32 v74, v1, v3
	v_cvt_pk_bf16_f32 v75, v71, v77
	v_cvt_pk_bf16_f32 v70, v2, v70
	v_cvt_pk_bf16_f32 v71, v76, v78
	ds_read_b128 v[76:79], v105 offset:8192
	ds_read_b128 v[80:83], v105 offset:9216
	ds_read_b128 v[84:87], v105 offset:24576
	ds_read_b128 v[88:91], v105 offset:25600
	s_and_b32 s98, s3, 0x180
	s_cbranch_scc1 .Lssmw_4
	s_waitcnt vmcnt(3)

; #define SSM_SCAN_STEP(D, SQ) { _Pragma("unroll") for (int r = 0; r < 4; ++r) { \
;                     const float sr = dppf<DPP_SHR(D)>(Er[r]), si = dppf<DPP_SHR(D)>(Ei[r]); \
;                     Er[r] += mr[r] * sr - mi[r] * si; Ei[r] += mr[r] * si + mi[r] * sr; \
;                     if (SQ) { const float nr = mr[r] * mr[r] - mi[r] * mi[r], ni = 2.f * mr[r] * mi[r]; mr[r] = nr; mi[r] = ni; } } }
; template <bool PASS2>
; __device__ __forceinline__ void ssm_phase(const Params& p, const Frame& F0) {
;     ...
;             for (int i = 0; i < 4; ++i) {
;                 __builtin_amdgcn_sched_barrier(0);
;                 f32x4 Er = (f32x4){0.f, 0.f, 0.f, 0.f}, Ei = Er;
; #pragma unroll
;                 for (int ks = 0; ks < 4; ++ks) { Er = __builtin_amdgcn_mfma_f32_16x16x32_bf16(frag[(i * 4 + ks) * 64], uf[ks], Er, 0, 0, 0);
;                                                  Ei = __builtin_amdgcn_mfma_f32_16x16x32_bf16(frag[((i + 4) * 4 + ks) * 64], uf[ks], Ei, 0, 0, 0); }
;                 const f32x4 ma = m1t[8 * i], mb = m1t[8 * i + 1];
;                 float mr[4] = {ma[0], ma[2], mb[0], mb[2]}, mi[4] = {ma[1], ma[3], mb[1], mb[3]};
;                 float hr[4], hi[4];
; #pragma unroll
;                 for (int r = 0; r < 4; ++r) { hr[r] = dppf<DPP_ROR(1)>(xs[i][r]); hi[r] = dppf<DPP_ROR(1)>(xs[i + 4][r]);
;                     if (j == 0) { Er[r] += mr[r] * hr[r] - mi[r] * hi[r]; Ei[r] += mr[r] * hi[r] + mi[r] * hr[r]; } }
;     ...
;                 SSM_SCAN_STEP(1, 1) SSM_SCAN_STEP(2, 1) SSM_SCAN_STEP(4, 1) SSM_SCAN_STEP(8, 0)
.Lssmw_5:
	v_mov_b32_dpp v2, v24 row_ror:1 row_mask:0xf bank_mask:0xf bound_ctrl:1
	s_waitcnt lgkmcnt(3)
	v_mfma_f32_16x16x32_bf16 v[76:79], v[76:79], v[56:59], 0
	v_mov_b32_dpp v201, v23 row_ror:1 row_mask:0xf bank_mask:0xf bound_ctrl:1
	v_mov_b32_dpp v200, v27 row_ror:1 row_mask:0xf bank_mask:0xf bound_ctrl:1
	s_waitcnt lgkmcnt(1)
	v_mfma_f32_16x16x32_bf16 v[84:87], v[84:87], v[56:59], 0
	v_mfma_f32_16x16x32_bf16 v[76:79], v[80:83], v[52:55], v[76:79]
	ds_read_b128 v[80:83], v105 offset:10240
	s_waitcnt lgkmcnt(1)
	v_mfma_f32_16x16x32_bf16 v[84:87], v[88:91], v[52:55], v[84:87]
	ds_read_b128 v[88:91], v105 offset:26624
	ds_read_b128 v[204:207], v105 offset:11264
	ds_read_b128 v[208:211], v105 offset:27648
	s_waitcnt lgkmcnt(2)
	v_mfma_f32_16x16x32_bf16 v[84:87], v[88:91], v[64:67], v[84:87]
	v_mov_b32_dpp v91, v22 row_ror:1 row_mask:0xf bank_mask:0xf bound_ctrl:1
	v_mov_b32_dpp v90, v26 row_ror:1 row_mask:0xf bank_mask:0xf bound_ctrl:1
	v_mfma_f32_16x16x32_bf16 v[76:79], v[80:83], v[64:67], v[76:79]
	ds_read_b128 v[80:83], v198 offset:256
	ds_read_b128 v[212:215], v198 offset:272
	ds_read_b128 v[216:219], v198 offset:1280
	ds_read_b128 v[220:223], v198 offset:1792
	s_waitcnt lgkmcnt(3)
	v_pk_mul_f32 v[88:89], v[80:81], v[2:3] op_sel:[0,1] op_sel_hi:[1,0]
	v_mfma_f32_16x16x32_bf16 v[84:87], v[208:211], v[60:63], v[84:87]
	v_sub_f32_e32 v1, v88, v89
	v_pk_mul_f32 v[88:89], v[80:81], v[2:3]
	v_mov_b32_e32 v208, v81
	v_mfma_f32_16x16x32_bf16 v[76:79], v[204:207], v[60:63], v[76:79]
	v_add_f32_e32 v20, v89, v88
	v_mov_b32_dpp v89, v21 row_ror:1 row_mask:0xf bank_mask:0xf bound_ctrl:1
	v_mov_b32_dpp v88, v25 row_ror:1 row_mask:0xf bank_mask:0xf bound_ctrl:1
	s_nop 0
	v_add_f32_e32 v24, v84, v20
	v_pk_mul_f32 v[20:21], v[82:83], v[88:89] op_sel:[0,1] op_sel_hi:[1,0]
	s_nop 1
	v_add_f32_e32 v1, v76, v1
	v_sub_f32_e32 v20, v20, v21
	v_add_f32_e32 v25, v20, v77
	v_pk_mul_f32 v[20:21], v[82:83], v[88:89]
	v_cndmask_b32_e64 v25, v77, v25, s[10:11]
	v_add_f32_e32 v20, v21, v20
	v_add_f32_e32 v199, v20, v85
	s_waitcnt lgkmcnt(2)
	v_pk_mul_f32 v[20:21], v[212:213], v[90:91] op_sel:[0,1] op_sel_hi:[1,0]
	v_mov_b32_e32 v204, v80
	v_sub_f32_e32 v20, v20, v21
	v_add_f32_e32 v26, v20, v78
	v_pk_mul_f32 v[20:21], v[212:213], v[90:91]
	v_cndmask_b32_e64 v26, v78, v26, s[10:11]
	v_add_f32_e32 v20, v21, v20
	v_add_f32_e32 v22, v20, v86
	v_pk_mul_f32 v[20:21], v[214:215], v[200:201] op_sel:[0,1] op_sel_hi:[1,0]
	v_mov_b32_e32 v205, v82
	v_sub_f32_e32 v20, v20, v21
	v_add_f32_e32 v27, v20, v79
	v_pk_mul_f32 v[20:21], v[214:215], v[200:201]
	v_cndmask_b32_e64 v27, v79, v27, s[10:11]
	v_add_f32_e32 v20, v21, v20
	v_add_f32_e32 v20, v20, v87
	v_cndmask_b32_e64 v23, v87, v20, s[10:11]
	v_cndmask_b32_e64 v21, v85, v199, s[10:11]
	v_cndmask_b32_e64 v20, v84, v24, s[10:11]
	v_cndmask_b32_e64 v24, v76, v1, s[10:11]
	v_mov_b32_dpp v79, v21 row_shr:1 row_mask:0xf bank_mask:0xf bound_ctrl:1
	v_mov_b32_dpp v78, v20 row_shr:1 row_mask:0xf bank_mask:0xf bound_ctrl:1
	v_mov_b32_dpp v76, v24 row_shr:1 row_mask:0xf bank_mask:0xf bound_ctrl:1
	v_mov_b32_dpp v77, v25 row_shr:1 row_mask:0xf bank_mask:0xf bound_ctrl:1
	v_pk_mul_f32 v[206:207], v[204:205], v[78:79]
	v_mov_b32_e32 v209, v83
	ds_read_b128 v[80:83], v198 offset:768
	v_pk_fma_f32 v[206:207], v[208:209], v[76:77], v[206:207]
	v_pk_add_f32 v[20:21], v[206:207], v[20:21]
	v_pk_fma_f32 v[24:25], v[208:209], v[78:79], v[24:25] neg_lo:[1,0,0] neg_hi:[1,0,0]
	v_pk_fma_f32 v[24:25], v[204:205], v[76:77], v[24:25]
	v_mov_b32_dpp v206, v20 row_shr:2 row_mask:0xf bank_mask:0xf bound_ctrl:1
	v_mov_b32_dpp v207, v21 row_shr:2 row_mask:0xf bank_mask:0xf bound_ctrl:1
	s_waitcnt lgkmcnt(0)
	v_pk_fma_f32 v[20:21], v[80:81], v[206:207], v[20:21]
	v_pk_mul_f32 v[78:79], v[82:83], v[206:207]
	v_mov_b32_dpp v76, v24 row_shr:2 row_mask:0xf bank_mask:0xf bound_ctrl:1
	v_mov_b32_dpp v77, v25 row_shr:2 row_mask:0xf bank_mask:0xf bound_ctrl:1
	v_pk_fma_f32 v[78:79], v[80:81], v[76:77], v[78:79] neg_lo:[0,0,1] neg_hi:[0,0,1]
	v_pk_fma_f32 v[20:21], v[82:83], v[76:77], v[20:21]
	ds_read_b64 v[82:83], v198 offset:792
	ds_read_b128 v[208:211], v198 offset:1296
	v_pk_add_f32 v[24:25], v[78:79], v[24:25]
	s_nop 0
	v_mov_b32_dpp v78, v20 row_shr:4 row_mask:0xf bank_mask:0xf bound_ctrl:1
	v_mov_b32_dpp v79, v21 row_shr:4 row_mask:0xf bank_mask:0xf bound_ctrl:1
	v_mov_b32_dpp v76, v24 row_shr:4 row_mask:0xf bank_mask:0xf bound_ctrl:1
	v_mov_b32_dpp v77, v25 row_shr:4 row_mask:0xf bank_mask:0xf bound_ctrl:1
	v_pk_mul_f32 v[80:81], v[218:219], v[78:79]
	v_pk_mul_f32 v[78:79], v[216:217], v[78:79]
	v_pk_fma_f32 v[80:81], v[216:217], v[76:77], v[80:81] neg_lo:[0,0,1] neg_hi:[0,0,1]
	v_pk_fma_f32 v[76:77], v[218:219], v[76:77], v[78:79]
	v_pk_add_f32 v[76:77], v[20:21], v[76:77]
	v_pk_add_f32 v[24:25], v[24:25], v[80:81]
	s_nop 0
	v_mov_b32_dpp v80, v76 row_shr:8 row_mask:0xf bank_mask:0xf bound_ctrl:1
	v_mov_b32_dpp v81, v77 row_shr:8 row_mask:0xf bank_mask:0xf bound_ctrl:1
	v_mov_b32_dpp v78, v24 row_shr:8 row_mask:0xf bank_mask:0xf bound_ctrl:1
	v_mov_b32_dpp v79, v25 row_shr:8 row_mask:0xf bank_mask:0xf bound_ctrl:1
	v_pk_mul_f32 v[20:21], v[222:223], v[80:81]
	v_cndmask_b32_e64 v22, v86, v22, s[10:11]
	v_pk_fma_f32 v[20:21], v[220:221], v[78:79], v[20:21] neg_lo:[0,0,1] neg_hi:[0,0,1]
	v_mov_b32_dpp v87, v23 row_shr:1 row_mask:0xf bank_mask:0xf bound_ctrl:1
	v_pk_add_f32 v[20:21], v[24:25], v[20:21]
	v_pk_mul_f32 v[24:25], v[220:221], v[80:81]
	v_mov_b32_dpp v86, v22 row_shr:1 row_mask:0xf bank_mask:0xf bound_ctrl:1
	v_pk_fma_f32 v[24:25], v[222:223], v[78:79], v[24:25]
	v_mov_b32_dpp v84, v26 row_shr:1 row_mask:0xf bank_mask:0xf bound_ctrl:1
	v_pk_add_f32 v[24:25], v[76:77], v[24:25]
	v_mov_b32_e32 v76, v212
	v_mov_b32_e32 v77, v214
	v_mov_b32_dpp v85, v27 row_shr:1 row_mask:0xf bank_mask:0xf bound_ctrl:1
	v_pk_mul_f32 v[78:79], v[76:77], v[86:87]
	v_mov_b32_e32 v80, v213
	v_mov_b32_e32 v81, v215
	ds_read_b128 v[212:215], v198 offset:1808
	v_pk_fma_f32 v[78:79], v[80:81], v[84:85], v[78:79]
	v_pk_add_f32 v[22:23], v[78:79], v[22:23]
	ds_read_b64 v[78:79], v198 offset:784
	v_pk_fma_f32 v[26:27], v[80:81], v[86:87], v[26:27] neg_lo:[1,0,0] neg_hi:[1,0,0]
	v_mov_b32_dpp v204, v22 row_shr:2 row_mask:0xf bank_mask:0xf bound_ctrl:1
	v_pk_fma_f32 v[26:27], v[76:77], v[84:85], v[26:27]
	v_mov_b32_dpp v205, v23 row_shr:2 row_mask:0xf bank_mask:0xf bound_ctrl:1
	s_waitcnt lgkmcnt(0)
; __device__ __forceinline__ unsigned cvt_pk_bf16(float lo, float hi) { unsigned r; asm("v_cvt_pk_bf16_f32 %0, %1, %2" : "=v"(r) : "v"(lo), "v"(hi)); return r; }
; #define SSM_SCAN_STEP(D, SQ) { _Pragma("unroll") for (int r = 0; r < 4; ++r) { \
;                     const float sr = dppf<DPP_SHR(D)>(Er[r]), si = dppf<DPP_SHR(D)>(Ei[r]); \
;                     Er[r] += mr[r] * sr - mi[r] * si; Ei[r] += mr[r] * si + mi[r] * sr; \
;                     if (SQ) { const float nr = mr[r] * mr[r] - mi[r] * mi[r], ni = 2.f * mr[r] * mi[r]; mr[r] = nr; mi[r] = ni; } } }
; template <bool PASS2>
; __device__ __forceinline__ void ssm_phase(const Params& p, const Frame& F0) {
;     ...
;                 SSM_SCAN_STEP(1, 1) SSM_SCAN_STEP(2, 1) SSM_SCAN_STEP(4, 1) SSM_SCAN_STEP(8, 0)
;     ...
;                 if constexpr (PASS2) {
;                     float vr[4], vi[4];
; #pragma unroll
;                     for (int r = 0; r < 4; ++r) { const float pr_ = dppf<DPP_ROR(1)>(Er[r]), pi_ = dppf<DPP_ROR(1)>(Ei[r]); vr[r] = (j == 0) ? hr[r] : pr_; vi[r] = (j == 0) ? hi[r] : pi_; }
;                     hw[i >> 1][2 * (i & 1)] = cvt_pk_bf16(vr[0], vr[1]); hw[i >> 1][2 * (i & 1) + 1] = cvt_pk_bf16(vr[2], vr[3]);
;                     hw[2 + (i >> 1)][2 * (i & 1)] = cvt_pk_bf16(vi[0], vi[1]); hw[2 + (i >> 1)][2 * (i & 1) + 1] = cvt_pk_bf16(vi[2], vi[3]);
;                 }
;                 xs[i] = Er; xs[i + 4] = Ei;
	v_pk_fma_f32 v[22:23], v[78:79], v[204:205], v[22:23]
	v_mov_b32_dpp v76, v26 row_shr:2 row_mask:0xf bank_mask:0xf bound_ctrl:1
	v_mov_b32_dpp v77, v27 row_shr:2 row_mask:0xf bank_mask:0xf bound_ctrl:1
	v_pk_fma_f32 v[26:27], v[82:83], v[204:205], v[26:27] neg_lo:[1,0,0] neg_hi:[1,0,0]
	v_pk_fma_f32 v[26:27], v[78:79], v[76:77], v[26:27]
	v_pk_fma_f32 v[22:23], v[82:83], v[76:77], v[22:23]
	s_nop 0
	s_nop 0
	v_mov_b32_dpp v78, v22 row_shr:4 row_mask:0xf bank_mask:0xf bound_ctrl:1
	v_mov_b32_dpp v79, v23 row_shr:4 row_mask:0xf bank_mask:0xf bound_ctrl:1
	v_mov_b32_dpp v76, v26 row_shr:4 row_mask:0xf bank_mask:0xf bound_ctrl:1
	v_mov_b32_dpp v77, v27 row_shr:4 row_mask:0xf bank_mask:0xf bound_ctrl:1
	v_pk_mul_f32 v[80:81], v[210:211], v[78:79]
	v_pk_mul_f32 v[78:79], v[208:209], v[78:79]
	v_pk_fma_f32 v[80:81], v[208:209], v[76:77], v[80:81] neg_lo:[0,0,1] neg_hi:[0,0,1]
	v_pk_fma_f32 v[76:77], v[210:211], v[76:77], v[78:79]
	v_pk_add_f32 v[76:77], v[22:23], v[76:77]
	v_pk_add_f32 v[26:27], v[26:27], v[80:81]
	s_nop 0
	v_mov_b32_dpp v80, v76 row_shr:8 row_mask:0xf bank_mask:0xf bound_ctrl:1
	v_mov_b32_dpp v81, v77 row_shr:8 row_mask:0xf bank_mask:0xf bound_ctrl:1
	v_mov_b32_dpp v78, v26 row_shr:8 row_mask:0xf bank_mask:0xf bound_ctrl:1
	v_mov_b32_dpp v79, v27 row_shr:8 row_mask:0xf bank_mask:0xf bound_ctrl:1
	v_pk_mul_f32 v[22:23], v[214:215], v[80:81]
	v_mov_b32_dpp v1, v20 row_ror:1 row_mask:0xf bank_mask:0xf bound_ctrl:1
	v_pk_fma_f32 v[22:23], v[212:213], v[78:79], v[22:23] neg_lo:[0,0,1] neg_hi:[0,0,1]
	v_cndmask_b32_e64 v1, v1, v3, s[10:11]
	v_pk_add_f32 v[22:23], v[26:27], v[22:23]
	v_pk_mul_f32 v[26:27], v[212:213], v[80:81]
	v_mov_b32_dpp v3, v21 row_ror:1 row_mask:0xf bank_mask:0xf bound_ctrl:1
	v_pk_fma_f32 v[26:27], v[214:215], v[78:79], v[26:27]
	v_mov_b32_dpp v79, v23 row_ror:1 row_mask:0xf bank_mask:0xf bound_ctrl:1
	v_pk_add_f32 v[26:27], v[76:77], v[26:27]
	v_mov_b32_dpp v76, v24 row_ror:1 row_mask:0xf bank_mask:0xf bound_ctrl:1
	v_cndmask_b32_e64 v2, v76, v2, s[10:11]
	v_mov_b32_dpp v77, v22 row_ror:1 row_mask:0xf bank_mask:0xf bound_ctrl:1
	v_mov_b32_dpp v76, v25 row_ror:1 row_mask:0xf bank_mask:0xf bound_ctrl:1
	v_mov_b32_dpp v78, v26 row_ror:1 row_mask:0xf bank_mask:0xf bound_ctrl:1
	v_mov_b32_dpp v80, v27 row_ror:1 row_mask:0xf bank_mask:0xf bound_ctrl:1
	v_cndmask_b32_e64 v76, v76, v88, s[10:11]
	v_cndmask_b32_e64 v77, v77, v91, s[10:11]
	v_cndmask_b32_e64 v78, v78, v90, s[10:11]
	v_cndmask_b32_e64 v79, v79, v201, s[10:11]
	v_cndmask_b32_e64 v82, v80, v200, s[10:11]
	v_cndmask_b32_e64 v3, v3, v89, s[10:11]
	v_cvt_pk_bf16_f32 v80, v1, v3
	v_cvt_pk_bf16_f32 v81, v77, v79
	v_cvt_pk_bf16_f32 v76, v2, v76
	v_cvt_pk_bf16_f32 v77, v78, v82
	ds_read_b128 v[82:85], v105 offset:12288
	ds_read_b128 v[86:89], v105 offset:13312
	ds_read_b128 v[204:207], v105 offset:28672
	ds_read_b128 v[208:211], v105 offset:29696
	v_mov_b32_dpp v3, v44 row_ror:1 row_mask:0xf bank_mask:0xf bound_ctrl:1
	s_and_b32 s98, s3, 0x180
	s_cbranch_scc1 .Lssmw_6
	s_waitcnt vmcnt(0)
.Lssmw_6:
	v_mov_b32_dpp v2, v48 row_ror:1 row_mask:0xf bank_mask:0xf bound_ctrl:1
	s_waitcnt lgkmcnt(3)
	v_mfma_f32_16x16x32_bf16 v[82:85], v[82:85], v[56:59], 0
	v_mov_b32_dpp v91, v46 row_ror:1 row_mask:0xf bank_mask:0xf bound_ctrl:1
	v_mov_b32_dpp v90, v50 row_ror:1 row_mask:0xf bank_mask:0xf bound_ctrl:1
	v_mov_b32_dpp v201, v47 row_ror:1 row_mask:0xf bank_mask:0xf bound_ctrl:1
	s_waitcnt lgkmcnt(1)
	v_mfma_f32_16x16x32_bf16 v[204:207], v[204:207], v[56:59], 0
	v_mov_b32_dpp v200, v51 row_ror:1 row_mask:0xf bank_mask:0xf bound_ctrl:1
	v_mfma_f32_16x16x32_bf16 v[82:85], v[86:89], v[52:55], v[82:85]
	ds_read_b128 v[86:89], v105 offset:14336
	s_waitcnt lgkmcnt(1)
	v_mfma_f32_16x16x32_bf16 v[204:207], v[208:211], v[52:55], v[204:207]
	ds_read_b128 v[208:211], v105 offset:30720
	ds_read_b128 v[212:215], v105 offset:15360
	ds_read_b128 v[216:219], v105 offset:31744
	s_waitcnt lgkmcnt(2)
	v_mfma_f32_16x16x32_bf16 v[204:207], v[208:211], v[64:67], v[204:207]
	v_mfma_f32_16x16x32_bf16 v[82:85], v[86:89], v[64:67], v[82:85]
	ds_read_b128 v[86:89], v198 offset:384
	ds_read_b128 v[220:223], v198 offset:400
	ds_read_b128 v[224:227], v198 offset:1920
	s_waitcnt lgkmcnt(2)
	v_pk_mul_f32 v[78:79], v[86:87], v[2:3] op_sel:[0,1] op_sel_hi:[1,0]
	v_mfma_f32_16x16x32_bf16 v[204:207], v[216:219], v[60:63], v[204:207]
	ds_read_b128 v[216:219], v198 offset:1408
	v_sub_f32_e32 v1, v78, v79
	v_pk_mul_f32 v[78:79], v[86:87], v[2:3]
	v_mov_b32_e32 v208, v86
	v_mfma_f32_16x16x32_bf16 v[82:85], v[212:215], v[60:63], v[82:85]
	v_add_f32_e32 v44, v79, v78
	v_mov_b32_dpp v79, v45 row_ror:1 row_mask:0xf bank_mask:0xf bound_ctrl:1
	v_mov_b32_dpp v78, v49 row_ror:1 row_mask:0xf bank_mask:0xf bound_ctrl:1
	s_nop 0
	v_add_f32_e32 v48, v204, v44
	v_pk_mul_f32 v[44:45], v[88:89], v[78:79] op_sel:[0,1] op_sel_hi:[1,0]
	s_nop 1
	v_add_f32_e32 v1, v82, v1
	v_sub_f32_e32 v44, v44, v45
	v_add_f32_e32 v49, v44, v83
	v_pk_mul_f32 v[44:45], v[88:89], v[78:79]
	v_cndmask_b32_e64 v49, v83, v49, s[10:11]
	v_add_f32_e32 v44, v45, v44
	v_add_f32_e32 v199, v44, v205
	s_waitcnt lgkmcnt(2)
; #define SSM_SCAN_STEP(D, SQ) { _Pragma("unroll") for (int r = 0; r < 4; ++r) { \
;                     const float sr = dppf<DPP_SHR(D)>(Er[r]), si = dppf<DPP_SHR(D)>(Ei[r]); \
;                     Er[r] += mr[r] * sr - mi[r] * si; Ei[r] += mr[r] * si + mi[r] * sr; \
;                     if (SQ) { const float nr = mr[r] * mr[r] - mi[r] * mi[r], ni = 2.f * mr[r] * mi[r]; mr[r] = nr; mi[r] = ni; } } }
; template <bool PASS2>
; __device__ __forceinline__ void ssm_phase(const Params& p, const Frame& F0) {
;     ...
;                 SSM_SCAN_STEP(1, 1) SSM_SCAN_STEP(2, 1) SSM_SCAN_STEP(4, 1) SSM_SCAN_STEP(8, 0)
	v_pk_mul_f32 v[44:45], v[220:221], v[90:91] op_sel:[0,1] op_sel_hi:[1,0]
	v_mov_b32_e32 v209, v88
	v_sub_f32_e32 v44, v44, v45
	v_add_f32_e32 v50, v44, v84
	v_pk_mul_f32 v[44:45], v[220:221], v[90:91]
	v_cndmask_b32_e64 v50, v84, v50, s[10:11]
	v_add_f32_e32 v44, v45, v44
	v_add_f32_e32 v46, v44, v206
	v_pk_mul_f32 v[44:45], v[222:223], v[200:201] op_sel:[0,1] op_sel_hi:[1,0]
	v_mov_b32_dpp v83, v49 row_shr:1 row_mask:0xf bank_mask:0xf bound_ctrl:1
	v_sub_f32_e32 v44, v44, v45
	v_add_f32_e32 v51, v44, v85
	v_pk_mul_f32 v[44:45], v[222:223], v[200:201]
	v_cndmask_b32_e64 v51, v85, v51, s[10:11]
	v_add_f32_e32 v44, v45, v44
	v_add_f32_e32 v44, v44, v207
	v_cndmask_b32_e64 v47, v207, v44, s[10:11]
	v_cndmask_b32_e64 v45, v205, v199, s[10:11]
	v_cndmask_b32_e64 v44, v204, v48, s[10:11]
	v_cndmask_b32_e64 v48, v82, v1, s[10:11]
	v_mov_b32_dpp v85, v45 row_shr:1 row_mask:0xf bank_mask:0xf bound_ctrl:1
	v_mov_b32_dpp v84, v44 row_shr:1 row_mask:0xf bank_mask:0xf bound_ctrl:1
	v_mov_b32_dpp v82, v48 row_shr:1 row_mask:0xf bank_mask:0xf bound_ctrl:1
	v_pk_mul_f32 v[210:211], v[208:209], v[84:85]
	v_mov_b32_e32 v212, v87
	v_mov_b32_e32 v213, v89
	ds_read_b128 v[86:89], v198 offset:896
	v_pk_fma_f32 v[210:211], v[212:213], v[82:83], v[210:211]
	v_pk_add_f32 v[44:45], v[210:211], v[44:45]
	v_pk_fma_f32 v[48:49], v[212:213], v[84:85], v[48:49] neg_lo:[1,0,0] neg_hi:[1,0,0]
	v_pk_fma_f32 v[48:49], v[208:209], v[82:83], v[48:49]
	v_mov_b32_dpp v210, v44 row_shr:2 row_mask:0xf bank_mask:0xf bound_ctrl:1
	v_mov_b32_dpp v211, v45 row_shr:2 row_mask:0xf bank_mask:0xf bound_ctrl:1
	s_waitcnt lgkmcnt(0)
	v_pk_fma_f32 v[44:45], v[86:87], v[210:211], v[44:45]
	v_pk_mul_f32 v[84:85], v[88:89], v[210:211]
	v_mov_b32_dpp v82, v48 row_shr:2 row_mask:0xf bank_mask:0xf bound_ctrl:1
	v_mov_b32_dpp v83, v49 row_shr:2 row_mask:0xf bank_mask:0xf bound_ctrl:1
	v_pk_fma_f32 v[84:85], v[86:87], v[82:83], v[84:85] neg_lo:[0,0,1] neg_hi:[0,0,1]
	v_pk_fma_f32 v[44:45], v[88:89], v[82:83], v[44:45]
	ds_read_b64 v[88:89], v198 offset:920
	ds_read_b128 v[212:215], v198 offset:1424
	v_pk_add_f32 v[48:49], v[84:85], v[48:49]
	s_nop 0
	v_mov_b32_dpp v84, v44 row_shr:4 row_mask:0xf bank_mask:0xf bound_ctrl:1
	v_mov_b32_dpp v85, v45 row_shr:4 row_mask:0xf bank_mask:0xf bound_ctrl:1
	v_mov_b32_dpp v82, v48 row_shr:4 row_mask:0xf bank_mask:0xf bound_ctrl:1
	v_mov_b32_dpp v83, v49 row_shr:4 row_mask:0xf bank_mask:0xf bound_ctrl:1
	v_pk_mul_f32 v[86:87], v[218:219], v[84:85]
	v_pk_mul_f32 v[84:85], v[216:217], v[84:85]
	v_pk_fma_f32 v[86:87], v[216:217], v[82:83], v[86:87] neg_lo:[0,0,1] neg_hi:[0,0,1]
	v_pk_fma_f32 v[82:83], v[218:219], v[82:83], v[84:85]
	ds_read_b128 v[216:219], v198 offset:1936
	v_pk_add_f32 v[82:83], v[44:45], v[82:83]
	v_pk_add_f32 v[48:49], v[48:49], v[86:87]
	s_nop 0
	v_mov_b32_dpp v86, v82 row_shr:8 row_mask:0xf bank_mask:0xf bound_ctrl:1
	v_mov_b32_dpp v87, v83 row_shr:8 row_mask:0xf bank_mask:0xf bound_ctrl:1
	v_mov_b32_dpp v84, v48 row_shr:8 row_mask:0xf bank_mask:0xf bound_ctrl:1
	v_mov_b32_dpp v85, v49 row_shr:8 row_mask:0xf bank_mask:0xf bound_ctrl:1
	v_pk_mul_f32 v[44:45], v[226:227], v[86:87]
	v_cndmask_b32_e64 v46, v206, v46, s[10:11]
	v_pk_fma_f32 v[44:45], v[224:225], v[84:85], v[44:45] neg_lo:[0,0,1] neg_hi:[0,0,1]
	v_mov_b32_dpp v207, v47 row_shr:1 row_mask:0xf bank_mask:0xf bound_ctrl:1
	v_pk_add_f32 v[44:45], v[48:49], v[44:45]
	v_pk_mul_f32 v[48:49], v[224:225], v[86:87]
	v_mov_b32_dpp v206, v46 row_shr:1 row_mask:0xf bank_mask:0xf bound_ctrl:1
	v_pk_fma_f32 v[48:49], v[226:227], v[84:85], v[48:49]
	v_mov_b32_dpp v204, v50 row_shr:1 row_mask:0xf bank_mask:0xf bound_ctrl:1
	v_pk_add_f32 v[48:49], v[82:83], v[48:49]
	v_mov_b32_e32 v82, v220
	v_mov_b32_e32 v83, v222
	v_mov_b32_dpp v205, v51 row_shr:1 row_mask:0xf bank_mask:0xf bound_ctrl:1
	v_pk_mul_f32 v[84:85], v[82:83], v[206:207]
	v_mov_b32_e32 v86, v221
	v_mov_b32_e32 v87, v223
	v_pk_fma_f32 v[84:85], v[86:87], v[204:205], v[84:85]
	v_pk_add_f32 v[46:47], v[84:85], v[46:47]
	ds_read_b64 v[84:85], v198 offset:912
	v_pk_fma_f32 v[50:51], v[86:87], v[206:207], v[50:51] neg_lo:[1,0,0] neg_hi:[1,0,0]
	v_mov_b32_dpp v208, v46 row_shr:2 row_mask:0xf bank_mask:0xf bound_ctrl:1
	v_pk_fma_f32 v[50:51], v[82:83], v[204:205], v[50:51]
	v_mov_b32_dpp v209, v47 row_shr:2 row_mask:0xf bank_mask:0xf bound_ctrl:1
	s_waitcnt lgkmcnt(0)
; __device__ __forceinline__ float bf_lo(unsigned w) { return __uint_as_float(w << 16); }
; template <bool PASS2>
; __device__ __forceinline__ void ssm_phase(const Params& p, const Frame& F0) {
;     ...
;                 SSM_SCAN_STEP(1, 1) SSM_SCAN_STEP(2, 1) SSM_SCAN_STEP(4, 1) SSM_SCAN_STEP(8, 0)
;     ...
;                 if constexpr (PASS2) {
;                     float vr[4], vi[4];
; #pragma unroll
;                     for (int r = 0; r < 4; ++r) { const float pr_ = dppf<DPP_ROR(1)>(Er[r]), pi_ = dppf<DPP_ROR(1)>(Ei[r]); vr[r] = (j == 0) ? hr[r] : pr_; vi[r] = (j == 0) ? hi[r] : pi_; }
;                     hw[i >> 1][2 * (i & 1)] = cvt_pk_bf16(vr[0], vr[1]); hw[i >> 1][2 * (i & 1) + 1] = cvt_pk_bf16(vr[2], vr[3]);
;                     hw[2 + (i >> 1)][2 * (i & 1)] = cvt_pk_bf16(vi[0], vi[1]); hw[2 + (i >> 1)][2 * (i & 1) + 1] = cvt_pk_bf16(vi[2], vi[3]);
;                 }
;                 xs[i] = Er; xs[i + 4] = Ei;
;             }
;             __builtin_amdgcn_sched_barrier(0);
;             asm volatile("" ::: "memory");
;             if constexpr (PASS2) {
;                 bf16x8 hf[4];
; #pragma unroll
;                 for (int kap = 0; kap < 4; ++kap) hf[kap] = __builtin_bit_cast(bf16x8, (u32x4){hw[kap][0], hw[kap][1], hw[kap][2], hw[kap][3]});
;                 const f32x4 dv = *(const f32x4*)(p.in[16] + g * 16 + 4 * gq);
; #pragma unroll
;                 for (int t = 0; t < 8; ++t) {
;                     asm volatile("" ::: "memory");
;                     f32x4 y = (f32x4){0.f, 0.f, 0.f, 0.f};
; #pragma unroll
;                     for (int ks = 0; ks < 4; ++ks) y = __builtin_amdgcn_mfma_f32_16x16x32_bf16(frag[(32 + t * 4 + ks) * 64], uf[ks], y, 0, 0, 0);
; #pragma unroll
;                     for (int kap = 0; kap < 4; ++kap) y = __builtin_amdgcn_mfma_f32_16x16x32_bf16(frag[(64 + t * 4 + kap) * 64], hf[kap], y, 0, 0, 0);
;                     if (j < nsub) {
;                         const size_t off = (size_t)(row0 + 8 * j + t) * DSSM + g * 16 + 4 * gq;
;                         const u32x2 uu = uw[t];
;                         const float z0 = gelu_tanh(y[0] + dv[0] * bf_lo(uu.x)), z1 = gelu_tanh(y[1] + dv[1] * bf_hi(uu.x)), z2 = gelu_tanh(y[2] + dv[2] * bf_lo(uu.y)), z3 = gelu_tanh(y[3] + dv[3] * bf_hi(uu.y));
;                         *(u32x2*)(Zb + off) = (u32x2){cvt_pk_bf16(z0, z1), cvt_pk_bf16(z2, z3)};
;                     }
	v_pk_fma_f32 v[46:47], v[84:85], v[208:209], v[46:47]
	v_mov_b32_dpp v82, v50 row_shr:2 row_mask:0xf bank_mask:0xf bound_ctrl:1
	v_mov_b32_dpp v83, v51 row_shr:2 row_mask:0xf bank_mask:0xf bound_ctrl:1
	v_pk_fma_f32 v[50:51], v[88:89], v[208:209], v[50:51] neg_lo:[1,0,0] neg_hi:[1,0,0]
	v_pk_fma_f32 v[50:51], v[84:85], v[82:83], v[50:51]
	v_pk_fma_f32 v[46:47], v[88:89], v[82:83], v[46:47]
	s_nop 0
	s_nop 0
	v_mov_b32_dpp v84, v46 row_shr:4 row_mask:0xf bank_mask:0xf bound_ctrl:1
	v_mov_b32_dpp v85, v47 row_shr:4 row_mask:0xf bank_mask:0xf bound_ctrl:1
	v_mov_b32_dpp v82, v50 row_shr:4 row_mask:0xf bank_mask:0xf bound_ctrl:1
	v_mov_b32_dpp v83, v51 row_shr:4 row_mask:0xf bank_mask:0xf bound_ctrl:1
	v_pk_mul_f32 v[86:87], v[214:215], v[84:85]
	v_pk_mul_f32 v[84:85], v[212:213], v[84:85]
	v_pk_fma_f32 v[86:87], v[212:213], v[82:83], v[86:87] neg_lo:[0,0,1] neg_hi:[0,0,1]
	v_pk_fma_f32 v[82:83], v[214:215], v[82:83], v[84:85]
	v_pk_add_f32 v[82:83], v[46:47], v[82:83]
	v_pk_add_f32 v[50:51], v[50:51], v[86:87]
	s_nop 0
	v_mov_b32_dpp v86, v82 row_shr:8 row_mask:0xf bank_mask:0xf bound_ctrl:1
	v_mov_b32_dpp v87, v83 row_shr:8 row_mask:0xf bank_mask:0xf bound_ctrl:1
	v_mov_b32_dpp v84, v50 row_shr:8 row_mask:0xf bank_mask:0xf bound_ctrl:1
	v_mov_b32_dpp v85, v51 row_shr:8 row_mask:0xf bank_mask:0xf bound_ctrl:1
	v_pk_mul_f32 v[46:47], v[218:219], v[86:87]
	v_mov_b32_dpp v1, v44 row_ror:1 row_mask:0xf bank_mask:0xf bound_ctrl:1
	v_pk_fma_f32 v[46:47], v[216:217], v[84:85], v[46:47] neg_lo:[0,0,1] neg_hi:[0,0,1]
	v_cndmask_b32_e64 v1, v1, v3, s[10:11]
	v_pk_add_f32 v[46:47], v[50:51], v[46:47]
	v_pk_mul_f32 v[50:51], v[216:217], v[86:87]
	v_mov_b32_dpp v3, v45 row_ror:1 row_mask:0xf bank_mask:0xf bound_ctrl:1
	v_pk_fma_f32 v[50:51], v[218:219], v[84:85], v[50:51]
	v_cndmask_b32_e64 v3, v3, v79, s[10:11]
	v_pk_add_f32 v[50:51], v[82:83], v[50:51]
	v_mov_b32_dpp v82, v48 row_ror:1 row_mask:0xf bank_mask:0xf bound_ctrl:1
	v_cndmask_b32_e64 v2, v82, v2, s[10:11]
	v_mov_b32_dpp v79, v46 row_ror:1 row_mask:0xf bank_mask:0xf bound_ctrl:1
	v_mov_b32_dpp v82, v49 row_ror:1 row_mask:0xf bank_mask:0xf bound_ctrl:1
	v_cndmask_b32_e64 v78, v82, v78, s[10:11]
	v_mov_b32_dpp v83, v51 row_ror:1 row_mask:0xf bank_mask:0xf bound_ctrl:1
	v_mov_b32_dpp v82, v50 row_ror:1 row_mask:0xf bank_mask:0xf bound_ctrl:1
	v_cndmask_b32_e64 v84, v82, v90, s[10:11]
	v_cndmask_b32_e64 v79, v79, v91, s[10:11]
	v_mov_b32_dpp v82, v47 row_ror:1 row_mask:0xf bank_mask:0xf bound_ctrl:1
	v_cndmask_b32_e64 v85, v82, v201, s[10:11]
	v_cndmask_b32_e64 v86, v83, v200, s[10:11]
	v_cvt_pk_bf16_f32 v82, v1, v3
	v_cvt_pk_bf16_f32 v83, v79, v85
	v_cvt_pk_bf16_f32 v78, v2, v78
	v_cvt_pk_bf16_f32 v79, v84, v86
	ds_read_b128 v[88:91], v105 offset:32768
	ds_read_b128 v[204:207], v105 offset:33792
	ds_read_b128 v[208:211], v105 offset:34816
	v_add_u32_e32 v2, s26, v159
	s_waitcnt lgkmcnt(2)
	v_mfma_f32_16x16x32_bf16 v[88:91], v[88:91], v[56:59], 0
	s_waitcnt lgkmcnt(1)
	v_mfma_f32_16x16x32_bf16 v[88:91], v[204:207], v[52:55], v[88:91]
	ds_read_b128 v[204:207], v105 offset:35840
	s_waitcnt lgkmcnt(1)
	v_mfma_f32_16x16x32_bf16 v[88:91], v[208:211], v[64:67], v[88:91]
	ds_read_b128 v[208:211], v164
	s_waitcnt lgkmcnt(1)
	v_mfma_f32_16x16x32_bf16 v[88:91], v[204:207], v[60:63], v[88:91]
	ds_read_b128 v[204:207], v165
	s_waitcnt lgkmcnt(1)
	v_mfma_f32_16x16x32_bf16 v[88:91], v[208:211], v[72:75], v[88:91]
	ds_read_b128 v[208:211], v166
	s_waitcnt lgkmcnt(1)
	v_mfma_f32_16x16x32_bf16 v[88:91], v[204:207], v[80:83], v[88:91]
	ds_read_b128 v[204:207], v167
	s_waitcnt lgkmcnt(1)
	v_mfma_f32_16x16x32_bf16 v[88:91], v[208:211], v[68:71], v[88:91]
	s_waitcnt lgkmcnt(0)
	v_mfma_f32_16x16x32_bf16 v[88:91], v[204:207], v[76:79], v[88:91]
	s_and_saveexec_b64 s[26:27], s[24:25]
	s_cbranch_execz .LBB0_648
	v_lshlrev_b32_e32 v1, 16, v156
	s_waitcnt vmcnt(0)
	s_nop 3
	v_fma_f32 v1, v228, v1, v88
	v_mul_f32_e32 v3, v1, v1
	v_fmamk_f32 v3, v3, 0xbdd2d3e8, v93
	v_mul_f32_e32 v3, v1, v3
	v_exp_f32_e32 v88, v3
	v_and_b32_e32 v3, 0xffff0000, v156
	v_lshlrev_b32_e32 v199, 16, v157
	v_and_b32_e32 v157, 0xffff0000, v157
	v_fma_f32 v89, v229, v3, v89
	v_fma_f32 v90, v230, v199, v90
	v_fmac_f32_e32 v91, v231, v157
	v_mul_f32_e32 v3, v89, v89
	v_mul_f32_e32 v199, v90, v90
	v_mul_f32_e32 v157, v91, v91
	v_fmamk_f32 v3, v3, 0xbdd2d3e8, v93
	v_fmamk_f32 v199, v199, 0xbdd2d3e8, v93
	v_fmamk_f32 v157, v157, 0xbdd2d3e8, v93
	v_mul_f32_e32 v3, v89, v3
	v_mul_f32_e32 v199, v90, v199
	v_mul_f32_e32 v157, v91, v157
	v_exp_f32_e32 v156, v3
	v_exp_f32_e32 v199, v199
	v_exp_f32_e32 v157, v157
	v_add_f32_e32 v88, 1.0, v88
	v_add_f32_e32 v156, 1.0, v156
	v_add_f32_e32 v199, 1.0, v199
	v_add_f32_e32 v157, 1.0, v157
	v_rcp_f32_e32 v88, v88
	v_rcp_f32_e32 v156, v156
	v_rcp_f32_e32 v199, v199
	v_rcp_f32_e32 v157, v157
	v_ashrrev_i32_e32 v3, 31, v2
	v_mul_f32_e32 v1, v1, v88
	v_mul_f32_e32 v88, v89, v156
	v_mul_f32_e32 v89, v90, v199
	v_mul_f32_e32 v90, v91, v157
	v_cvt_pk_bf16_f32 v89, v89, v90
	v_lshlrev_b64 v[90:91], 10, v[2:3]
	v_lshl_add_u64 v[90:91], v[134:135], 0, v[90:91]
	v_cvt_pk_bf16_f32 v88, v1, v88
	global_store_dwordx2 v[90:91], v[88:89], off
